# barrier_waiters_poll_global_generation
# baseline (speedup 1.0000x reference)
.LBB0_88:
	s_lshl_b32 s0, s33, 8
	s_add_u32 s23, s34, s0
	s_addc_u32 s22, s35, 0
	v_mov_b32_e32 v1, s23
	v_add_co_u32_e32 v6, vcc, 0x1000, v1
	v_mov_b32_e32 v1, s22
	s_nop 0
	v_addc_co_u32_e32 v7, vcc, 0, v1, vcc
	v_mov_b32_e32 v1, 1
	flat_atomic_add v1, v[6:7], v1 offset:1024 sc0
	v_cvt_f32_u32_e32 v3, v4
	v_sub_u32_e32 v5, 0, v4
	v_rcp_iflag_f32_e32 v3, v3
	s_nop 0
	v_mul_f32_e32 v3, 0x4f7ffffe, v3
	v_cvt_u32_f32_e32 v3, v3
	v_mul_lo_u32 v5, v5, v3
	v_mul_hi_u32 v5, v3, v5
	v_add_u32_e32 v3, v3, v5
	s_waitcnt vmcnt(0) lgkmcnt(0)
	v_mul_hi_u32 v3, v1, v3
	v_mul_lo_u32 v5, v3, v4
	v_add_u32_e32 v6, 1, v1
	v_sub_u32_e32 v1, v1, v5
	v_add_u32_e32 v7, 1, v3
	v_cmp_ge_u32_e32 vcc, v1, v4
	v_sub_u32_e32 v5, v1, v4
	s_nop 0
	v_cndmask_b32_e32 v3, v3, v7, vcc
	v_cndmask_b32_e32 v1, v1, v5, vcc
	v_add_u32_e32 v5, 1, v3
	v_cmp_ge_u32_e32 vcc, v1, v4
	s_nop 1
	v_cndmask_b32_e32 v1, v3, v5, vcc
	v_mad_u64_u32 v[4:5], s[0:1], v4, v1, v[4:5]
	v_cmp_ne_u32_e32 vcc, v6, v4
	s_and_saveexec_b64 s[0:1], vcc
	s_xor_b64 s[0:1], exec, s[0:1]
	s_cbranch_execz .LBB0_101
	v_mov_b32_e32 v2, s34
	v_add_co_u32_e32 v2, vcc, 0x3100, v2
	v_mov_b32_e32 v3, s35
	s_nop 0
	v_addc_co_u32_e32 v3, vcc, 0, v3, vcc
	flat_load_dword v2, v[2:3] offset:1024 sc1
	s_add_u32 s6, s34, 0x3500
	s_addc_u32 s7, s35, 0
	s_waitcnt vmcnt(0) lgkmcnt(0)
	v_cmp_eq_u32_e32 vcc, v2, v1
	s_and_saveexec_b64 s[4:5], vcc
	s_cbranch_execz .LBB0_100
	s_mov_b32 s24, 1
	s_mov_b64 s[8:9], 0
	s_branch .LBB0_92

.LBB0_353:
	v_readlane_b32 s6, v254, 47
	s_lshl_b32 s6, s6, 2
	s_add_u32 s27, s4, s6
	s_addc_u32 s26, s5, 0
	v_mov_b32_e32 v3, s27
	v_add_co_u32_e32 v6, vcc, 0x1000, v3
	v_mov_b32_e32 v3, s26
	s_nop 0
	v_addc_co_u32_e32 v7, vcc, 0, v3, vcc
	flat_atomic_add v5, v[6:7], v1 offset:1024 sc0
	v_cvt_f32_u32_e32 v3, v4
	v_sub_u32_e32 v6, 0, v4
	v_rcp_iflag_f32_e32 v3, v3
	s_nop 0
	v_mul_f32_e32 v3, 0x4f7ffffe, v3
	v_cvt_u32_f32_e32 v3, v3
	v_mul_lo_u32 v6, v6, v3
	v_mul_hi_u32 v6, v3, v6
	v_add_u32_e32 v3, v3, v6
	s_waitcnt vmcnt(0) lgkmcnt(0)
	v_mul_hi_u32 v3, v5, v3
	v_mul_lo_u32 v6, v3, v4
	v_sub_u32_e32 v6, v5, v6
	v_cmp_ge_u32_e32 vcc, v6, v4
	v_add_u32_e32 v7, 1, v3
	s_nop 0
	v_cndmask_b32_e32 v3, v3, v7, vcc
	v_sub_u32_e32 v7, v6, v4
	v_cndmask_b32_e32 v6, v6, v7, vcc
	v_cmp_ge_u32_e32 vcc, v6, v4
	v_add_u32_e32 v6, 1, v3
	s_nop 0
	v_cndmask_b32_e32 v3, v3, v6, vcc
	v_add_u32_e32 v6, 1, v5
	v_mad_u64_u32 v[4:5], s[6:7], v4, v3, v[4:5]
	v_cmp_ne_u32_e32 vcc, v6, v4
	s_and_saveexec_b64 s[6:7], vcc
	s_xor_b64 s[6:7], exec, s[6:7]
	s_cbranch_execz .LBB0_366
	v_mov_b32_e32 v2, s4
	v_add_co_u32_e32 v4, vcc, 0x3100, v2
	v_mov_b32_e32 v2, s5
	s_nop 0
	v_addc_co_u32_e32 v5, vcc, 0, v2, vcc
	flat_load_dword v2, v[4:5] offset:1024 sc1
	s_add_u32 s10, s4, 0x3500
	s_addc_u32 s11, s5, 0
	s_waitcnt vmcnt(0) lgkmcnt(0)
	v_cmp_eq_u32_e32 vcc, v2, v3
	s_and_saveexec_b64 s[8:9], vcc
	s_cbranch_execz .LBB0_365
	s_mov_b32 s28, 1
	s_mov_b64 s[12:13], 0
	s_branch .LBB0_357
